# phase-0 conversion offload ranges rounded to whole rounds of the item loop (16384/18432/20480: 8 items per wave in phase 0, 2 per idle wave per slot) on top of v71
# speedup vs baseline: 1.0045x; 1.0012x over previous
.LBB0_20:
	s_lshr_b32 s89, s77, 6
	s_load_dwordx16 s[8:23], s[0:1], 0x40
	s_cmp_lt_i32 s28, 1
	s_cselect_b64 s[0:1], -1, 0
	s_cmp_gt_i32 s29, 0
	s_cselect_b64 s[2:3], -1, 0
	s_and_b64 s[2:3], s[0:1], s[2:3]
	s_andn2_b64 vcc, exec, s[2:3]
	v_and_b32_e32 v227, 63, v226
	s_cbranch_vccnz .LBB0_42
	s_mov_b32 s96, 0
	s_mov_b32 s97, 0x4000
	s_lshl_b32 s0, s76, 3
	s_add_i32 s4, s0, s89

.Lp0call_1:
	v_writelane_b32 v251, s0, 0
	v_writelane_b32 v251, s1, 1
	v_writelane_b32 v251, s4, 2
	v_writelane_b32 v251, s5, 3
	v_writelane_b32 v251, s26, 4
	v_writelane_b32 v251, s27, 5
	v_writelane_b32 v251, s30, 6
	v_writelane_b32 v251, s31, 7
	v_writelane_b32 v251, s34, 8
	v_writelane_b32 v251, s35, 9
	v_writelane_b32 v251, s52, 10
	v_writelane_b32 v251, s53, 11
	v_writelane_b32 v251, s54, 12
	v_writelane_b32 v251, s55, 13
	v_writelane_b32 v251, s56, 14
	v_writelane_b32 v251, s57, 15
	v_writelane_b32 v251, s58, 16
	v_writelane_b32 v251, s59, 17
	v_writelane_b32 v251, s60, 18
	v_writelane_b32 v251, s61, 19
	v_writelane_b32 v251, s62, 20
	v_writelane_b32 v251, s63, 21
	v_writelane_b32 v251, s64, 22
	v_writelane_b32 v251, s65, 23
	v_writelane_b32 v251, s66, 24
	v_writelane_b32 v251, s67, 25
	v_writelane_b32 v251, s68, 26
	v_writelane_b32 v251, s69, 27
	v_writelane_b32 v251, s70, 28
	v_writelane_b32 v251, s71, 29
	v_writelane_b32 v251, s33, 30
	v_writelane_b32 v251, s40, 31
	v_writelane_b32 v251, s41, 32
	v_writelane_b32 v251, s42, 33
	v_writelane_b32 v251, s43, 34
	v_writelane_b32 v251, s89, 35
	v_writelane_b32 v251, vcc_lo, 36
	v_writelane_b32 v251, vcc_hi, 37
	s_nop 1
	v_readlane_b32 s0, v250, 0
	v_readlane_b32 s1, v250, 1
	s_nop 3
	s_sub_u32 s0, s0, 0x90
	s_subb_u32 s1, s1, 0
	s_load_dwordx4 s[40:43], s[0:1], 0x10
	s_lshr_b32 s89, s77, 6
	s_sub_i32 s4, s6, 0x80
	s_lshl_b32 s4, s4, 3
	s_add_i32 s4, s4, s89
	s_add_i32 s4, s4, 0x4000
	s_mov_b32 s33, 0x80
	s_mov_b32 s97, 0x4800
	s_mov_b32 s96, 1
	s_waitcnt vmcnt(0) lgkmcnt(0)
	s_branch .Lp0_entry

.Lp0call_2:
	v_writelane_b32 v251, s0, 0
	v_writelane_b32 v251, s1, 1
	v_writelane_b32 v251, s4, 2
	v_writelane_b32 v251, s5, 3
	v_writelane_b32 v251, s26, 4
	v_writelane_b32 v251, s27, 5
	v_writelane_b32 v251, s30, 6
	v_writelane_b32 v251, s31, 7
	v_writelane_b32 v251, s34, 8
	v_writelane_b32 v251, s35, 9
	v_writelane_b32 v251, s52, 10
	v_writelane_b32 v251, s53, 11
	v_writelane_b32 v251, s54, 12
	v_writelane_b32 v251, s55, 13
	v_writelane_b32 v251, s56, 14
	v_writelane_b32 v251, s57, 15
	v_writelane_b32 v251, s58, 16
	v_writelane_b32 v251, s59, 17
	v_writelane_b32 v251, s60, 18
	v_writelane_b32 v251, s61, 19
	v_writelane_b32 v251, s62, 20
	v_writelane_b32 v251, s63, 21
	v_writelane_b32 v251, s64, 22
	v_writelane_b32 v251, s65, 23
	v_writelane_b32 v251, s66, 24
	v_writelane_b32 v251, s67, 25
	v_writelane_b32 v251, s68, 26
	v_writelane_b32 v251, s69, 27
	v_writelane_b32 v251, s70, 28
	v_writelane_b32 v251, s71, 29
	v_writelane_b32 v251, s33, 30
	v_writelane_b32 v251, s40, 31
	v_writelane_b32 v251, s41, 32
	v_writelane_b32 v251, s42, 33
	v_writelane_b32 v251, s43, 34
	v_writelane_b32 v251, s89, 35
	v_writelane_b32 v251, vcc_lo, 36
	v_writelane_b32 v251, vcc_hi, 37
	s_nop 1
	v_readlane_b32 s0, v250, 0
	v_readlane_b32 s1, v250, 1
	s_nop 3
	s_sub_u32 s0, s0, 0x90
	s_subb_u32 s1, s1, 0
	s_load_dwordx4 s[40:43], s[0:1], 0x10
	s_lshr_b32 s89, s77, 6
	s_sub_i32 s4, s6, 0x80
	s_lshl_b32 s4, s4, 3
	s_add_i32 s4, s4, s89
	s_add_i32 s4, s4, 0x4800
	s_mov_b32 s33, 0x80
	s_mov_b32 s97, 0x5000
	s_mov_b32 s96, 2
	s_waitcnt vmcnt(0) lgkmcnt(0)
	s_branch .Lp0_entry

.Lp0call_3:
	v_writelane_b32 v251, s0, 0
	v_writelane_b32 v251, s1, 1
	v_writelane_b32 v251, s4, 2
	v_writelane_b32 v251, s5, 3
	v_writelane_b32 v251, s26, 4
	v_writelane_b32 v251, s27, 5
	v_writelane_b32 v251, s30, 6
	v_writelane_b32 v251, s31, 7
	v_writelane_b32 v251, s34, 8
	v_writelane_b32 v251, s35, 9
	v_writelane_b32 v251, s52, 10
	v_writelane_b32 v251, s53, 11
	v_writelane_b32 v251, s54, 12
	v_writelane_b32 v251, s55, 13
	v_writelane_b32 v251, s56, 14
	v_writelane_b32 v251, s57, 15
	v_writelane_b32 v251, s58, 16
	v_writelane_b32 v251, s59, 17
	v_writelane_b32 v251, s60, 18
	v_writelane_b32 v251, s61, 19
	v_writelane_b32 v251, s62, 20
	v_writelane_b32 v251, s63, 21
	v_writelane_b32 v251, s64, 22
	v_writelane_b32 v251, s65, 23
	v_writelane_b32 v251, s66, 24
	v_writelane_b32 v251, s67, 25
	v_writelane_b32 v251, s68, 26
	v_writelane_b32 v251, s69, 27
	v_writelane_b32 v251, s70, 28
	v_writelane_b32 v251, s71, 29
	v_writelane_b32 v251, s33, 30
	v_writelane_b32 v251, s40, 31
	v_writelane_b32 v251, s41, 32
	v_writelane_b32 v251, s42, 33
	v_writelane_b32 v251, s43, 34
	v_writelane_b32 v251, s89, 35
	v_writelane_b32 v251, vcc_lo, 36
	v_writelane_b32 v251, vcc_hi, 37
	s_nop 1
	v_readlane_b32 s0, v250, 0
	v_readlane_b32 s1, v250, 1
	s_nop 3
	s_sub_u32 s0, s0, 0x90
	s_subb_u32 s1, s1, 0
	s_load_dwordx4 s[40:43], s[0:1], 0x10
	s_lshr_b32 s89, s77, 6
	s_sub_i32 s4, s6, 0x80
	s_lshl_b32 s4, s4, 3
	s_add_i32 s4, s4, s89
	s_add_i32 s4, s4, 0x5000
	s_mov_b32 s33, 0x80
	s_mov_b32 s97, 0x5800
	s_mov_b32 s96, 3
	s_waitcnt vmcnt(0) lgkmcnt(0)
	s_branch .Lp0_entry
